# S5 pass-C entry reads the pass-A counter before draining its own stores (one round trip off the transition)
# speedup vs baseline: 1.0133x; 1.0002x over previous
.LBB0_1031:
	s_mov_b64 s[6:7], s[0:1]
	s_and_saveexec_b64 s[4:5], s[38:39]
	s_load_dwordx2 s[18:19], s[0:1], 0xe8
	v_mov_b32_e32 v0, 0
	s_waitcnt lgkmcnt(0)
	s_add_u32 s18, s18, 0x779be00
	s_addc_u32 s19, s19, 0
	global_load_dword v2, v0, s[18:19] sc1
	s_or_b64 exec, exec, s[4:5]
	s_waitcnt vmcnt(0)
	s_barrier
	s_and_saveexec_b64 s[4:5], s[38:39]
	s_cbranch_execz .LBB0_1083
	s_mov_b32 s22, 0
	s_branch .Lp4_chk

.Lp4_chk:
	v_readfirstlane_b32 s23, v2
	s_cmpk_ge_u32 s23, 0x100
	s_cbranch_scc1 .Lp4_w_ok
	s_sleep 1
	s_add_i32 s22, s22, 1
	s_cmp_lt_u32 s22, 0x40000
	s_cbranch_scc1 .Lp4_w
